# MoBA key-mean reduction: 8 loads in flight per step instead of one waited load at a time (same summation order)
# speedup vs baseline: 1.0175x; 1.0147x over previous
.LBB0_1297:
	s_and_b32 s19, s1, 0x100
	s_and_b32 s20, s5, 24
	s_and_b32 s18, s4, 0x3000
	s_or_b32 s19, s19, s20
	s_lshl_b32 s19, s19, 4
	s_lshl_b32 s18, s18, 1
	s_or_b32 s36, s19, s18
	v_lshl_add_u64 v[12:13], v[10:11], 0, s[36:37]
	global_load_ushort v46, v[12:13], off
	global_load_ushort v47, v[12:13], off offset:16
	global_load_ushort v48, v[12:13], off offset:32
	global_load_ushort v49, v[12:13], off offset:48
	global_load_ushort v50, v[12:13], off offset:64
	global_load_ushort v51, v[12:13], off offset:80
	global_load_ushort v52, v[12:13], off offset:96
	global_load_ushort v53, v[12:13], off offset:112
	s_add_i32 s5, s5, 8
	s_addk_i32 s4, 0x200
	s_add_i32 s1, s1, 64
	s_cmpk_eq_i32 s5, 0x100
	s_waitcnt vmcnt(0)
	v_lshlrev_b32_e32 v46, 16, v46
	v_add_f32_e32 v0, v0, v46
	v_lshlrev_b32_e32 v47, 16, v47
	v_add_f32_e32 v0, v0, v47
	v_lshlrev_b32_e32 v48, 16, v48
	v_add_f32_e32 v0, v0, v48
	v_lshlrev_b32_e32 v49, 16, v49
	v_add_f32_e32 v0, v0, v49
	v_lshlrev_b32_e32 v50, 16, v50
	v_add_f32_e32 v0, v0, v50
	v_lshlrev_b32_e32 v51, 16, v51
	v_add_f32_e32 v0, v0, v51
	v_lshlrev_b32_e32 v52, 16, v52
	v_add_f32_e32 v0, v0, v52
	v_lshlrev_b32_e32 v53, 16, v53
	v_add_f32_e32 v0, v0, v53
	s_cbranch_scc0 .LBB0_1297
	s_lshl_b64 s[2:3], s[2:3], 8
	v_mul_f32_e32 v0, 0x3b800000, v0
	v_lshl_add_u64 v[10:11], v[4:5], 0, s[2:3]
	global_store_dword v[10:11], v0, off
	s_branch .LBB0_1294
